# attention tile loop stagger: waves 4..7 take each tile barrier in front of their 16-exp tail (rescale flag compressed to one SGPR, second SGPR selects the wave half)
# baseline (speedup 1.0000x reference)
.LBB0_422:
	s_lshl_b32 s0, s39, 10
	s_and_b32 s6, s0, 0x800000
	s_lshl_b32 s0, s43, 1
	s_and_b32 s66, s0, 0x300
	s_lshl_b32 s0, s64, 11
	s_lshl_b32 s1, s64, 4
	s_and_b32 s0, s0, 0x2000
	s_and_b32 s1, s1, 0xffffff80
	s_add_i32 s1, s0, s1
	v_or_b32_e32 v171, s1, v170
	v_or_b32_e32 v0, v171, v169
	v_ashrrev_i32_e32 v1, 31, v0
	s_lshl_b32 s1, s64, 7
	v_lshlrev_b64 v[0:1], 10, v[0:1]
	s_and_b32 s65, s1, 0x180
	v_lshl_add_u64 v[0:1], s[86:87], 0, v[0:1]
	s_lshl_b32 s4, s65, 1
	s_mov_b32 s5, s7
	v_lshl_add_u64 v[0:1], v[0:1], 0, s[4:5]
	s_lshl_b32 s5, s0, 10
	s_add_u32 s0, s33, s5
	s_addc_u32 s1, s34, 0
	s_add_u32 s0, s0, s4
	v_mov_b32_e32 v174, v168
	v_lshl_add_u64 v[0:1], v[160:161], 1, v[0:1]
	s_addc_u32 s1, s1, 0
	v_lshl_add_u64 v[0:1], v[0:1], 0, v[162:163]
	v_ashrrev_i32_e32 v16, 4, v174
	s_add_u32 s5, s35, s5
	v_lshlrev_b32_e32 v20, 3, v174
	v_add_u32_e32 v18, 32, v16
	s_addc_u32 s16, s38, 0
	global_load_dwordx4 v[124:127], v[0:1], off
	global_load_dwordx4 v[120:123], v[0:1], off offset:32
	global_load_dwordx4 v[116:119], v[0:1], off offset:64
	global_load_dwordx4 v[112:115], v[0:1], off offset:96
	v_and_b32_e32 v0, 0x78, v20
	v_ashrrev_i32_e32 v17, 31, v16
	v_ashrrev_i32_e32 v19, 31, v18
	s_add_u32 s4, s5, s4
	v_lshlrev_b32_e32 v21, 1, v0
	v_lshlrev_b64 v[48:49], 10, v[16:17]
	v_lshlrev_b64 v[12:13], 10, v[18:19]
	s_addc_u32 s5, s16, 0
	v_or_b32_e32 v50, v48, v21
	v_mov_b32_e32 v51, v49
	v_or_b32_e32 v12, v12, v21
	v_lshl_add_u64 v[0:1], s[4:5], 0, v[50:51]
	v_lshl_add_u64 v[4:5], s[4:5], 0, v[12:13]
	s_barrier
	global_load_dwordx4 v[0:3], v[0:1], off
	s_nop 0
	global_load_dwordx4 v[4:7], v[4:5], off
	v_lshl_add_u64 v[8:9], s[0:1], 0, v[50:51]
	global_load_dwordx4 v[8:11], v[8:9], off
	v_lshl_add_u64 v[12:13], s[0:1], 0, v[12:13]
	global_load_dwordx4 v[12:15], v[12:13], off
	v_and_b32_e32 v22, 0xfffff0, v16
	v_lshlrev_b32_e32 v23, 1, v16
	v_lshrrev_b32_e32 v24, 1, v16
	v_and_b32_e32 v25, 3, v16
	v_and_or_b32 v22, v23, 8, v22
	v_and_or_b32 v23, v24, 4, v25
	v_and_b32_e32 v24, 0xfffff0, v18
	v_lshlrev_b32_e32 v25, 1, v18
	v_and_b32_e32 v17, 0x70, v174
	v_bfe_u32 v20, v20, 5, 2
	v_lshlrev_b32_e32 v16, 8, v16
	v_lshrrev_b32_e32 v22, 1, v22
	v_and_or_b32 v24, v25, 8, v24
	v_bitop3_b32 v183, v21, v16, v17 bitop3:0xde
	v_or_b32_e32 v16, v22, v20
	v_lshrrev_b32_e32 v22, 1, v24
	v_lshlrev_b32_e32 v23, 6, v23
	v_and_b32_e32 v26, 48, v21
	v_lshlrev_b32_e32 v16, 9, v16
	v_or_b32_e32 v20, v22, v20
	v_or3_b32 v184, v16, v23, v26
	v_lshlrev_b32_e32 v16, 9, v20
	v_bfe_u32 v172, v174, 5, 1
	v_ashrrev_i32_e32 v175, 8, v174
	v_lshlrev_b32_e32 v52, 4, v174
	v_or3_b32 v186, v16, v23, v26
	v_add_u32_e32 v84, 16, v184
	v_and_b32_e32 v173, 31, v174
	v_lshlrev_b32_e32 v19, 7, v175
	v_add_u32_e32 v24, 16, v183
	v_add_u32_e32 v85, 16, v186
	s_waitcnt vmcnt(0)
	v_lshlrev_b32_e32 v176, 4, v172
	v_lshlrev_b32_e32 v190, 8, v173
	v_and_b32_e32 v86, 63, v174
	v_lshl_add_u64 v[60:61], v[50:51], 0, s[14:15]
	v_lshl_add_u64 v[64:65], v[50:51], 0, s[36:37]
	v_lshl_add_u64 v[56:57], s[4:5], 0, v[64:65]
	v_lshl_add_u64 v[64:65], s[0:1], 0, v[64:65]
	s_cmp_lg_u32 16, -1
	s_cselect_b32 s16, 16, 0
	s_mov_b32 s17, s7
	s_mov_b32 s18, s7
	s_mov_b32 s19, s7
	s_mov_b32 s20, s7
	s_waitcnt vmcnt(3)
	ds_write_b128 v84, v[0:3]
	s_waitcnt vmcnt(2)
	ds_write_b128 v85, v[4:7]
	s_waitcnt vmcnt(1)
	ds_write_b128 v24, v[8:11] offset:49152
	v_and_b32_e32 v8, 0x70, v52
	v_lshlrev_b32_e32 v0, 8, v18
	v_bitop3_b32 v182, v176, v8, v19 bitop3:0x36
	v_bitop3_b32 v188, v21, v0, v17 bitop3:0xde
	v_add_u32_e32 v185, v182, v190
	v_add_u32_e32 v0, 16, v188
	v_add_u32_e32 v4, 16, v185
	s_waitcnt vmcnt(0)
	ds_write_b128 v0, v[12:15] offset:49152
	s_waitcnt lgkmcnt(0)
	s_barrier
	ds_read_b128 v[0:3], v4 offset:49152
	ds_read_b128 v[4:7], v4 offset:57344
	v_or_b32_e32 v9, v176, v19
	v_bitop3_b32 v187, v9, v8, 32 bitop3:0x36
	v_add_u32_e32 v189, v187, v190
	s_waitcnt lgkmcnt(0)
	v_mfma_f32_32x32x16_bf16 v[16:31], v[4:7], v[124:127], 0
	v_add_u32_e32 v4, 16, v189
	v_bitop3_b32 v193, v9, v8, s3 bitop3:0x36
	v_bitop3_b32 v191, v9, v8, 64 bitop3:0x36
	v_add_u32_e32 v194, v193, v190
	v_add_u32_e32 v192, v191, v190
	v_add_u32_e32 v8, 16, v194
	v_and_b32_e32 v5, 0x3fffffc0, v174
	v_mfma_f32_32x32x16_bf16 v[32:47], v[0:3], v[124:127], 0
	ds_read_b128 v[0:3], v4 offset:49152
	v_and_b32_e32 v11, 0xc0, v52
	v_add_u32_e32 v13, 16, v192
	ds_read_b128 v[52:55], v8 offset:57344
	v_lshl_add_u32 v177, v5, 2, s50
	ds_read_b128 v[4:7], v4 offset:57344
	v_lshlrev_b32_e32 v10, 3, v86
	s_waitcnt lgkmcnt(2)
	v_mfma_f32_32x32x16_bf16 v[32:47], v[0:3], v[120:123], v[32:47]
	v_lshlrev_b32_e32 v0, 1, v174
	v_and_b32_e32 v12, 32, v0
	ds_read_b128 v[0:3], v13 offset:49152
	v_and_or_b32 v11, v10, 24, v11
	s_mov_b32 s21, s7
	s_mov_b32 s22, s7
	s_mov_b32 s23, s7
	s_waitcnt lgkmcnt(0)
	v_mfma_f32_32x32x16_bf16 v[32:47], v[0:3], v[116:119], v[32:47]
	ds_read_b128 v[0:3], v8 offset:49152
	s_mov_b32 s24, s7
	s_mov_b32 s25, s7
	s_mov_b32 s26, s7
	s_mov_b32 s27, s7
	s_mov_b32 s28, s7
	s_mov_b32 s29, s7
	v_mfma_f32_32x32x16_bf16 v[16:31], v[4:7], v[120:123], v[16:31]
	v_and_b32_e32 v4, 0x100, v10
	v_lshlrev_b32_e32 v4, 3, v4
	v_or3_b32 v178, v11, v12, v4
	ds_read_b128 v[4:7], v13 offset:57344
	v_add_u32_e32 v181, s16, v178
	s_mov_b32 s16, s7
	s_mov_b32 s30, s7
	s_mov_b32 s31, s7
	s_waitcnt lgkmcnt(0)
	v_mfma_f32_32x32x16_bf16 v[16:31], v[4:7], v[116:119], v[16:31]
	v_lshl_add_u32 v179, v173, 2, v177
	v_mov_b32_e32 v196, 1.0
	v_mov_b32_e32 v180, 0
	v_mfma_f32_32x32x16_bf16 v[32:47], v[0:3], v[112:115], v[32:47]
	v_mov_b64_e32 v[0:1], s[16:17]
	v_mov_b64_e32 v[14:15], s[30:31]
	v_mov_b64_e32 v[2:3], s[18:19]
	v_mov_b64_e32 v[4:5], s[20:21]
	v_mov_b64_e32 v[6:7], s[22:23]
	v_mov_b64_e32 v[8:9], s[24:25]
	v_mov_b64_e32 v[10:11], s[26:27]
	v_mfma_f32_32x32x16_bf16 v[16:31], v[52:55], v[112:115], v[16:31]
	s_nop 3
	v_max_f32_e32 v52, v33, v33
	v_max_f32_e32 v53, v32, v32
	v_max_f32_e32 v52, v53, v52
	v_max3_f32 v52, v52, v34, v35
	v_max3_f32 v52, v52, v36, v37
	v_max3_f32 v52, v52, v38, v39
	v_max3_f32 v52, v52, v40, v41
	v_max3_f32 v52, v52, v42, v43
	v_max3_f32 v52, v52, v44, v45
	v_max3_f32 v66, v52, v46, v47
	v_lshl_add_u64 v[52:53], s[4:5], 0, v[60:61]
	v_lshl_add_u64 v[60:61], s[0:1], 0, v[60:61]
	global_load_dwordx4 v[52:55], v[52:53], off
	s_nop 0
	global_load_dwordx4 v[56:59], v[56:57], off
	v_mov_b64_e32 v[12:13], s[28:29]
	global_load_dwordx4 v[60:63], v[60:61], off
	s_mov_b32 s19, 1
	global_load_dwordx4 v[80:83], v[64:65], off
	v_max3_f32 v64, v66, v16, v17
	v_max3_f32 v64, v64, v18, v19
	v_max3_f32 v64, v64, v20, v21
	v_max3_f32 v64, v64, v22, v23
	v_max3_f32 v64, v64, v24, v25
	v_max3_f32 v64, v64, v26, v27
	v_max3_f32 v64, v64, v28, v29
	v_max3_f32 v70, v64, v30, v31
	v_lshl_add_u64 v[64:65], v[50:51], 0, s[40:41]
	v_lshl_add_u64 v[66:67], s[0:1], 0, v[64:65]
	v_lshl_add_u64 v[50:51], v[50:51], 0, s[44:45]
	v_lshl_add_u64 v[64:65], s[4:5], 0, v[64:65]
	v_lshl_add_u64 v[68:69], s[0:1], 0, v[50:51]
	global_load_dwordx4 v[136:139], v[66:67], off
	global_load_dwordx4 v[128:131], v[68:69], off
	v_lshl_add_u64 v[50:51], s[4:5], 0, v[50:51]
	global_load_dwordx4 v[140:143], v[64:65], off
	global_load_dwordx4 v[132:135], v[50:51], off
	v_mov_b32_e32 v71, v70
	s_nop 1
	v_permlane32_swap_b32_e32 v70, v71
	v_max_f32_e32 v50, v71, v71
	v_max_f32_e32 v51, v70, v70
	v_max_f32_e32 v50, v51, v50
	v_sub_f32_e32 v64, v16, v50
	v_add_u32_e32 v16, s58, v183
	v_sub_f32_e32 v32, v32, v50
	v_sub_f32_e32 v33, v33, v50
	v_sub_f32_e32 v34, v34, v50
	v_sub_f32_e32 v35, v35, v50
	v_sub_f32_e32 v36, v36, v50
	v_sub_f32_e32 v37, v37, v50
	v_sub_f32_e32 v38, v38, v50
	v_sub_f32_e32 v39, v39, v50
	v_sub_f32_e32 v40, v40, v50
	v_sub_f32_e32 v41, v41, v50
	v_sub_f32_e32 v42, v42, v50
	v_sub_f32_e32 v43, v43, v50
	v_sub_f32_e32 v44, v44, v50
	v_sub_f32_e32 v45, v45, v50
	v_sub_f32_e32 v46, v46, v50
	v_sub_f32_e32 v47, v47, v50
	v_sub_f32_e32 v66, v18, v50
	s_waitcnt vmcnt(4)
	s_waitcnt vmcnt(7)
	ds_write_b128 v84, v[52:55] offset:16384
	s_waitcnt vmcnt(6)
	ds_write_b128 v85, v[56:59] offset:16384
	v_and_b32_e32 v18, 15, v174
	s_waitcnt vmcnt(5)
	ds_write_b128 v16, v[60:63]
	v_add_u32_e32 v16, s58, v188
	v_sub_f32_e32 v65, v17, v50
	v_exp_f32_e32 v152, v32
	v_exp_f32_e32 v153, v33
	v_exp_f32_e32 v154, v34
	v_exp_f32_e32 v155, v35
	v_exp_f32_e32 v156, v36
	v_exp_f32_e32 v157, v37
	v_exp_f32_e32 v158, v38
	v_exp_f32_e32 v159, v39
	v_exp_f32_e32 v144, v40
	v_exp_f32_e32 v145, v41
	v_exp_f32_e32 v146, v42
	v_exp_f32_e32 v147, v43
	v_exp_f32_e32 v148, v44
	v_exp_f32_e32 v149, v45
	v_exp_f32_e32 v150, v46
	v_exp_f32_e32 v151, v47
	s_waitcnt vmcnt(4)
	ds_write_b128 v16, v[80:83]
	v_lshl_add_u64 v[16:17], s[6:7], 0, v[48:49]
	v_lshlrev_b32_e32 v18, 4, v18
	v_or3_b32 v16, v16, s66, v18
	v_add_f32_e32 v195, 0, v50
	v_sub_f32_e32 v79, v31, v50
	v_sub_f32_e32 v78, v30, v50
	v_sub_f32_e32 v77, v29, v50
	v_sub_f32_e32 v76, v28, v50
	v_sub_f32_e32 v75, v27, v50
	v_sub_f32_e32 v74, v26, v50
	v_sub_f32_e32 v73, v25, v50
	v_sub_f32_e32 v72, v24, v50
	v_sub_f32_e32 v71, v23, v50
	v_sub_f32_e32 v70, v22, v50
	v_sub_f32_e32 v69, v21, v50
	v_sub_f32_e32 v68, v20, v50
	v_sub_f32_e32 v67, v19, v50
	v_lshl_add_u64 v[166:167], s[12:13], 0, v[16:17]
	v_mov_b64_e32 v[62:63], v[14:15]
	v_mov_b64_e32 v[46:47], v[14:15]
	v_mov_b64_e32 v[30:31], v[14:15]
	v_cmp_gt_u32_e64 s[0:1], 32, v86
	v_mov_b64_e32 v[60:61], v[12:13]
	v_mov_b64_e32 v[58:59], v[10:11]
	v_mov_b64_e32 v[56:57], v[8:9]
	v_mov_b64_e32 v[54:55], v[6:7]
	v_mov_b64_e32 v[52:53], v[4:5]
	v_mov_b64_e32 v[50:51], v[2:3]
	v_mov_b64_e32 v[48:49], v[0:1]
	v_mov_b64_e32 v[44:45], v[12:13]
	v_mov_b64_e32 v[42:43], v[10:11]
	v_mov_b64_e32 v[40:41], v[8:9]
	v_mov_b64_e32 v[38:39], v[6:7]
	v_mov_b64_e32 v[36:37], v[4:5]
	v_mov_b64_e32 v[34:35], v[2:3]
	v_mov_b64_e32 v[32:33], v[0:1]
	v_mov_b64_e32 v[28:29], v[12:13]
	v_mov_b64_e32 v[26:27], v[10:11]
	v_mov_b64_e32 v[24:25], v[8:9]
	v_mov_b64_e32 v[22:23], v[6:7]
	v_mov_b64_e32 v[20:21], v[4:5]
	v_mov_b64_e32 v[18:19], v[2:3]
	v_mov_b64_e32 v[16:17], v[0:1]
	s_mov_b32 s6, 1
	s_mov_b32 s18, 0
	s_waitcnt lgkmcnt(0)
	s_barrier
	v_add_co_u32_e32 v242, vcc, s61, v166
	s_nop 1
	v_addc_co_u32_e32 v243, vcc, -1, v167, vcc
	s_nop 0
	v_readfirstlane_b32 s98, v242
	v_readfirstlane_b32 s99, v243
	s_nop 1
	v_subrev_u32_e32 v242, s98, v242
	v_add_u32_e32 v243, 0x8000, v242
	v_add_u32_e32 v244, 0x1000000, v242
	v_add_u32_e32 v245, 0x1008000, v242
	v_readfirstlane_b32 s101, v214
	s_lshr_b32 s101, s101, 8
.LBB0_423:
	s_lshl_b32 s16, s19, 14
	s_add_i32 s4, s16, 16
	v_add_u32_e32 v96, s4, v185
	ds_read_b128 v[198:201], v96 offset:49152
	ds_read_b128 v[202:205], v96 offset:57344
	v_xor_b32_e32 v80, 0x80000000, v195
	v_mov_b32_e32 v81, v80
	v_mov_b64_e32 v[82:83], v[80:81]
	v_mov_b64_e32 v[84:85], v[80:81]
	v_mov_b64_e32 v[86:87], v[80:81]
	v_mov_b64_e32 v[88:89], v[80:81]
	v_mov_b64_e32 v[90:91], v[80:81]
	v_mov_b64_e32 v[92:93], v[80:81]
	v_mov_b64_e32 v[94:95], v[80:81]
	v_exp_f32_e32 v221, v64
	s_waitcnt lgkmcnt(1)
	v_mfma_f32_32x32x16_bf16 v[96:111], v[198:201], v[124:127], v[80:95]
	v_add_f32_e32 v64, v153, v152
	v_add_f32_e32 v64, v154, v64
	v_add_u32_e32 v197, s4, v189
	v_add_f32_e32 v64, v155, v64
	v_add_f32_e32 v64, v156, v64
	v_add_f32_e32 v64, v157, v64
	v_add_f32_e32 v64, v158, v64
	s_waitcnt lgkmcnt(0)
	v_mfma_f32_32x32x16_bf16 v[80:95], v[202:205], v[124:127], v[80:95]
	ds_read_b128 v[198:201], v197 offset:49152
	ds_read_b128 v[202:205], v197 offset:57344
	v_add_f32_e32 v64, v159, v64
	v_add_f32_e32 v64, v144, v64
	v_add_f32_e32 v64, v145, v64
	v_add_f32_e32 v64, v146, v64
	v_add_u32_e32 v197, s4, v192
	v_add_f32_e32 v64, v147, v64
	s_waitcnt lgkmcnt(1)
	v_mfma_f32_32x32x16_bf16 v[96:111], v[198:201], v[120:123], v[96:111]
	ds_read_b128 v[198:201], v197 offset:49152
	ds_read_b128 v[206:209], v197 offset:57344
	v_add_f32_e32 v64, v148, v64
	v_exp_f32_e32 v222, v65
	v_add_f32_e32 v64, v149, v64
	v_exp_f32_e32 v223, v66
	v_add_f32_e32 v64, v150, v64
	v_exp_f32_e32 v224, v67
	s_waitcnt lgkmcnt(2)
	v_mfma_f32_32x32x16_bf16 v[80:95], v[202:205], v[120:123], v[80:95]
	v_add_f32_e32 v64, v151, v64
	v_add_f32_e32 v64, v221, v64
	v_add_f32_e32 v64, v222, v64
	v_add_f32_e32 v64, v223, v64
	v_exp_f32_e32 v71, v71
	v_add_f32_e32 v64, v224, v64
	v_add_u32_e32 v197, s4, v194
	s_waitcnt lgkmcnt(1)
	v_mfma_f32_32x32x16_bf16 v[96:111], v[198:201], v[116:119], v[96:111]
	v_exp_f32_e32 v199, v68
	v_exp_f32_e32 v200, v69
	v_exp_f32_e32 v201, v70
	v_exp_f32_e32 v225, v72
	v_add_f32_e32 v64, v199, v64
	ds_read_b128 v[202:205], v197 offset:49152
	ds_read_b128 v[210:213], v197 offset:57344
	v_exp_f32_e32 v226, v73
	s_waitcnt lgkmcnt(2)
	v_mfma_f32_32x32x16_bf16 v[80:95], v[206:209], v[116:119], v[80:95]
	v_add_f32_e32 v64, v200, v64
	v_exp_f32_e32 v227, v74
	v_add_f32_e32 v64, v201, v64
	v_exp_f32_e32 v206, v75
	v_add_f32_e32 v64, v71, v64
	v_exp_f32_e32 v207, v76
	v_add_f32_e32 v64, v225, v64
	v_exp_f32_e32 v208, v77
	v_add_f32_e32 v64, v226, v64
	v_exp_f32_e32 v209, v78
	s_waitcnt lgkmcnt(1)
	v_mfma_f32_32x32x16_bf16 v[96:111], v[202:205], v[112:115], v[96:111]
	v_add_f32_e32 v64, v227, v64
	v_exp_f32_e32 v79, v79
	v_add_f32_e32 v64, v206, v64
	v_add_f32_e32 v64, v207, v64
	v_add_f32_e32 v64, v208, v64
	v_add_f32_e32 v64, v209, v64
	v_add_f32_e32 v197, v79, v64
	s_waitcnt lgkmcnt(0)
	v_mfma_f32_32x32x16_bf16 v[80:95], v[210:213], v[112:115], v[80:95]
	v_cvt_pk_bf16_f32 v64, v152, v153
	v_cvt_pk_bf16_f32 v65, v154, v155
	v_cvt_pk_bf16_f32 v66, v156, v157
	v_cvt_pk_bf16_f32 v67, v158, v159
	v_cvt_pk_bf16_f32 v72, v144, v145
	v_cvt_pk_bf16_f32 v73, v146, v147
	v_cvt_pk_bf16_f32 v74, v148, v149
	v_cvt_pk_bf16_f32 v75, v150, v151
	v_cvt_pk_bf16_f32 v68, v221, v222
	v_cvt_pk_bf16_f32 v69, v223, v224
	v_cvt_pk_bf16_f32 v70, v199, v200
	v_cvt_pk_bf16_f32 v71, v201, v71
	v_cvt_pk_bf16_f32 v76, v225, v226
	v_cvt_pk_bf16_f32 v77, v227, v206
	v_cvt_pk_bf16_f32 v78, v207, v208
	v_cvt_pk_bf16_f32 v79, v209, v79
	global_load_dwordx4 v[144:147], v244, s[98:99]
	global_load_dwordx4 v[148:151], v245, s[98:99]
	global_load_dwordx4 v[152:155], v242, s[98:99]
	global_load_dwordx4 v[156:159], v243, s[98:99]
	s_add_u32 s98, s98, 0x10000
	s_addc_u32 s99, s99, 0
	v_lshl_add_u32 v199, s18, 14, v181
	ds_read_b64_tr_b16 v[200:201], v199 offset:0
	ds_read_b64_tr_b16 v[202:203], v199 offset:0x100
	ds_read_b64_tr_b16 v[204:205], v199 offset:0x1000
	ds_read_b64_tr_b16 v[206:207], v199 offset:0x1100
	ds_read_b64_tr_b16 v[208:209], v199 offset:0x2000
	ds_read_b64_tr_b16 v[210:211], v199 offset:0x2100
	ds_read_b64_tr_b16 v[222:223], v199 offset:0x3000
	ds_read_b64_tr_b16 v[224:225], v199 offset:0x3100
	s_waitcnt lgkmcnt(6)
	v_mfma_f32_32x32x16_bf16 v[0:15], v[64:67], v[200:203], v[0:15]
	v_max_f32_e32 v200, v96, v97
	v_max3_f32 v200, v200, v98, v99
	v_max3_f32 v200, v200, v100, v101
	v_max3_f32 v200, v200, v102, v103
	v_max3_f32 v200, v200, v104, v105
	s_waitcnt lgkmcnt(4)
	v_mfma_f32_32x32x16_bf16 v[0:15], v[72:75], v[204:207], v[0:15]
	v_max3_f32 v200, v200, v106, v107
	v_max3_f32 v202, v200, v108, v109
	ds_read_b64_tr_b16 v[200:201], v199 offset:0x200
	v_max3_f32 v212, v202, v110, v111
	ds_read_b64_tr_b16 v[202:203], v199 offset:0x300
	ds_read_b64_tr_b16 v[204:205], v199 offset:0x1200
	ds_read_b64_tr_b16 v[206:207], v199 offset:0x1300
	s_waitcnt lgkmcnt(6)
	v_mfma_f32_32x32x16_bf16 v[0:15], v[68:71], v[208:211], v[0:15]
	ds_read_b64_tr_b16 v[208:209], v199 offset:0x2200
	ds_read_b64_tr_b16 v[210:211], v199 offset:0x2300
	ds_read_b64_tr_b16 v[226:227], v199 offset:0x3200
	ds_read_b64_tr_b16 v[228:229], v199 offset:0x3300
	s_waitcnt lgkmcnt(8)
	v_mfma_f32_32x32x16_bf16 v[0:15], v[76:79], v[222:225], v[0:15]
	s_waitcnt lgkmcnt(6)
	v_mfma_f32_32x32x16_bf16 v[48:63], v[64:67], v[200:203], v[48:63]
	v_max3_f32 v212, v212, v80, v81
	v_max3_f32 v200, v212, v82, v83
	ds_read_b64_tr_b16 v[202:203], v199 offset:0x400
	v_max3_f32 v200, v200, v84, v85
	v_max3_f32 v200, v200, v86, v87
	v_max3_f32 v200, v200, v88, v89
	v_max3_f32 v200, v200, v90, v91
	s_waitcnt lgkmcnt(5)
	v_mfma_f32_32x32x16_bf16 v[48:63], v[72:75], v[204:207], v[48:63]
	ds_read_b64_tr_b16 v[204:205], v199 offset:0x500
	ds_read_b64_tr_b16 v[206:207], v199 offset:0x1400
	v_max3_f32 v200, v200, v92, v93
	v_max3_f32 v200, v200, v94, v95
	s_waitcnt lgkmcnt(5)
	v_mfma_f32_32x32x16_bf16 v[48:63], v[68:71], v[208:211], v[48:63]
	ds_read_b64_tr_b16 v[208:209], v199 offset:0x1500
	ds_read_b64_tr_b16 v[210:211], v199 offset:0x2400
	ds_read_b64_tr_b16 v[212:213], v199 offset:0x2500
	ds_read_b64_tr_b16 v[222:223], v199 offset:0x3400
	ds_read_b64_tr_b16 v[224:225], v199 offset:0x3500
	s_waitcnt lgkmcnt(8)
	v_mfma_f32_32x32x16_bf16 v[48:63], v[76:79], v[226:229], v[48:63]
	s_waitcnt lgkmcnt(6)
	v_mfma_f32_32x32x16_bf16 v[32:47], v[64:67], v[202:205], v[32:47]
	v_cmp_ge_f32_e32 vcc, s63, v200
	s_cmp_eq_u64 vcc, exec
	s_waitcnt lgkmcnt(4)
	v_mfma_f32_32x32x16_bf16 v[32:47], v[72:75], v[206:209], v[32:47]
	s_waitcnt lgkmcnt(2)
	v_mfma_f32_32x32x16_bf16 v[32:47], v[68:71], v[210:213], v[32:47]
	s_waitcnt lgkmcnt(0)
	v_mfma_f32_32x32x16_bf16 v[32:47], v[76:79], v[222:225], v[32:47]
	s_cbranch_scc0 .LBB0_438
	v_mov_b32_e32 v200, 1.0
	s_mov_b32 s100, 0
.LBB0_425:
	ds_read_b64_tr_b16 v[202:203], v199 offset:0x600
	ds_read_b64_tr_b16 v[204:205], v199 offset:0x700
	ds_read_b64_tr_b16 v[206:207], v199 offset:0x1600
	ds_read_b64_tr_b16 v[208:209], v199 offset:0x1700
	ds_read_b64_tr_b16 v[210:211], v199 offset:0x2600
	ds_read_b64_tr_b16 v[212:213], v199 offset:0x2700
	ds_read_b64_tr_b16 v[222:223], v199 offset:0x3600
	ds_read_b64_tr_b16 v[224:225], v199 offset:0x3700
	s_add_i32 s4, s19, 1
	s_cmp_lg_u32 s19, 2
	s_cselect_b32 s18, s4, 0
	s_waitcnt lgkmcnt(6)
	v_mfma_f32_32x32x16_bf16 v[16:31], v[64:67], v[202:205], v[16:31]
	s_lshl_b32 s4, s18, 14
	s_add_i32 s17, s4, 16
	v_add_u32_e32 v64, s17, v184
	s_waitcnt vmcnt(4)
	s_waitcnt vmcnt(4)
	ds_write_b128 v64, v[132:135]
	v_add_u32_e32 v64, s17, v186
	ds_write_b128 v64, v[140:143]
	s_waitcnt lgkmcnt(6)
	v_mfma_f32_32x32x16_bf16 v[16:31], v[72:75], v[206:209], v[16:31]
	v_add_u32_e32 v64, s17, v183
	ds_write_b128 v64, v[128:131] offset:49152
	v_add_u32_e32 v64, s17, v188
	ds_write_b128 v64, v[136:139] offset:49152
	s_waitcnt lgkmcnt(6)
	v_mfma_f32_32x32x16_bf16 v[16:31], v[68:71], v[210:213], v[16:31]
	s_waitcnt lgkmcnt(4)
	v_mfma_f32_32x32x16_bf16 v[16:31], v[76:79], v[222:225], v[16:31]
	s_cmp_eq_u32 s101, 0
	s_cbranch_scc1 .Lst_a0_e0
	s_waitcnt lgkmcnt(0)
	s_barrier
.Lst_a0_e0:
	s_cmp_eq_u32 s100, 0
	s_cbranch_scc1 .LBB0_429
	s_and_saveexec_b64 s[4:5], s[0:1]
	ds_write_b32 v179, v200 offset:128
	s_or_b64 exec, exec, s[4:5]
	s_waitcnt lgkmcnt(0)
	v_add_u32_e32 v76, v177, v176
	ds_read_b128 v[64:67], v76 offset:224
	ds_read_b128 v[68:71], v76 offset:192
	ds_read_b128 v[72:75], v76 offset:160
	ds_read_b128 v[76:79], v76 offset:128
	s_waitcnt lgkmcnt(3)
	v_pk_mul_f32 v[12:13], v[12:13], v[64:65]
	s_waitcnt lgkmcnt(2)
	v_pk_mul_f32 v[8:9], v[8:9], v[68:69]
	s_waitcnt lgkmcnt(1)
	v_pk_mul_f32 v[4:5], v[4:5], v[72:73]
	v_pk_mul_f32 v[14:15], v[14:15], v[66:67]
	v_pk_mul_f32 v[10:11], v[10:11], v[70:71]
	v_pk_mul_f32 v[6:7], v[6:7], v[74:75]
	s_waitcnt lgkmcnt(0)
	v_pk_mul_f32 v[2:3], v[2:3], v[78:79]
	v_pk_mul_f32 v[0:1], v[0:1], v[76:77]
	v_pk_mul_f32 v[60:61], v[60:61], v[64:65]
	v_pk_mul_f32 v[56:57], v[56:57], v[68:69]
	v_pk_mul_f32 v[52:53], v[52:53], v[72:73]
	v_pk_mul_f32 v[62:63], v[62:63], v[66:67]
	v_pk_mul_f32 v[58:59], v[58:59], v[70:71]
	v_pk_mul_f32 v[54:55], v[54:55], v[74:75]
	v_pk_mul_f32 v[50:51], v[50:51], v[78:79]
	v_pk_mul_f32 v[48:49], v[48:49], v[76:77]
	v_pk_mul_f32 v[44:45], v[44:45], v[64:65]
	v_pk_mul_f32 v[40:41], v[40:41], v[68:69]
	v_pk_mul_f32 v[36:37], v[36:37], v[72:73]
	v_pk_mul_f32 v[46:47], v[46:47], v[66:67]
	v_pk_mul_f32 v[42:43], v[42:43], v[70:71]
	v_pk_mul_f32 v[38:39], v[38:39], v[74:75]
	v_pk_mul_f32 v[34:35], v[34:35], v[78:79]
	v_pk_mul_f32 v[32:33], v[32:33], v[76:77]
	v_pk_mul_f32 v[28:29], v[28:29], v[64:65]
	v_pk_mul_f32 v[24:25], v[24:25], v[68:69]
	v_pk_mul_f32 v[20:21], v[20:21], v[72:73]
	v_pk_mul_f32 v[30:31], v[30:31], v[66:67]
	v_pk_mul_f32 v[26:27], v[26:27], v[70:71]
	v_pk_mul_f32 v[22:23], v[22:23], v[74:75]
	v_pk_mul_f32 v[18:19], v[18:19], v[78:79]
	v_pk_mul_f32 v[16:17], v[16:17], v[76:77]
.LBB0_429:
	v_exp_f32_e32 v199, v96
	v_exp_f32_e32 v221, v97
	v_exp_f32_e32 v226, v98
	v_exp_f32_e32 v227, v99
	v_exp_f32_e32 v228, v100
	v_exp_f32_e32 v229, v101
	v_exp_f32_e32 v230, v102
	v_exp_f32_e32 v231, v103
	v_exp_f32_e32 v232, v104
	v_exp_f32_e32 v233, v105
	v_exp_f32_e32 v234, v106
	v_exp_f32_e32 v235, v107
	v_exp_f32_e32 v236, v108
	v_exp_f32_e32 v237, v109
	v_exp_f32_e32 v238, v110
	v_exp_f32_e32 v239, v111
	s_waitcnt lgkmcnt(0)
	s_cmp_lg_u32 s101, 0
	s_cbranch_scc1 .Lst_a0_l0
	s_barrier
.Lst_a0_l0:
	v_add_u32_e32 v96, s17, v185
	ds_read_b128 v[202:205], v96 offset:49152
	ds_read_b128 v[206:209], v96 offset:57344
	v_xor_b32_e32 v64, 0x80000000, v195
	v_mov_b32_e32 v65, v64
	v_mov_b64_e32 v[66:67], v[64:65]
	v_mov_b64_e32 v[68:69], v[64:65]
	v_mov_b64_e32 v[70:71], v[64:65]
	v_mov_b64_e32 v[72:73], v[64:65]
	v_mov_b64_e32 v[74:75], v[64:65]
	v_mov_b64_e32 v[76:77], v[64:65]
	v_mov_b64_e32 v[78:79], v[64:65]
	v_add_u32_e32 v201, s17, v189
	v_exp_f32_e32 v80, v80
	s_waitcnt lgkmcnt(1)
	v_mfma_f32_32x32x16_bf16 v[96:111], v[202:205], v[124:127], v[64:79]
	v_exp_f32_e32 v81, v81
	v_exp_f32_e32 v82, v82
	v_exp_f32_e32 v83, v83
	v_exp_f32_e32 v84, v84
	v_exp_f32_e32 v85, v85
	v_exp_f32_e32 v86, v86
	v_exp_f32_e32 v87, v87
	s_waitcnt lgkmcnt(0)
	v_mfma_f32_32x32x16_bf16 v[64:79], v[206:209], v[124:127], v[64:79]
	ds_read_b128 v[202:205], v201 offset:49152
	ds_read_b128 v[206:209], v201 offset:57344
	v_add_u32_e32 v201, s17, v192
	v_exp_f32_e32 v240, v91
	v_exp_f32_e32 v241, v92
	v_cvt_pk_bf16_f32 v91, v230, v231
	v_cvt_pk_bf16_f32 v92, v232, v233
	s_waitcnt lgkmcnt(1)
	v_mfma_f32_32x32x16_bf16 v[96:111], v[202:205], v[120:123], v[96:111]
	ds_read_b128 v[202:205], v201 offset:49152
	ds_read_b128 v[210:213], v201 offset:57344
	v_add_u32_e32 v201, s17, v194
	s_waitcnt lgkmcnt(1)
	v_mfma_f32_32x32x16_bf16 v[96:111], v[202:205], v[116:119], v[96:111]
	v_exp_f32_e32 v203, v88
	v_add_f32_e32 v88, v221, v199
	v_add_f32_e32 v88, v226, v88
	v_add_f32_e32 v88, v227, v88
	v_add_f32_e32 v88, v228, v88
	v_add_f32_e32 v88, v229, v88
	v_add_f32_e32 v88, v230, v88
	v_add_f32_e32 v88, v231, v88
	v_add_f32_e32 v88, v232, v88
	v_add_f32_e32 v88, v233, v88
	v_mfma_f32_32x32x16_bf16 v[64:79], v[206:209], v[120:123], v[64:79]
	v_add_f32_e32 v88, v234, v88
	v_add_f32_e32 v88, v235, v88
	v_add_f32_e32 v88, v236, v88
	v_add_f32_e32 v88, v237, v88
	v_add_f32_e32 v88, v238, v88
	v_add_f32_e32 v88, v239, v88
	v_add_f32_e32 v88, v80, v88
	v_add_f32_e32 v88, v81, v88
	s_waitcnt lgkmcnt(0)
	v_mfma_f32_32x32x16_bf16 v[64:79], v[210:213], v[116:119], v[64:79]
	v_add_f32_e32 v88, v82, v88
	v_add_f32_e32 v88, v83, v88
	v_add_f32_e32 v88, v84, v88
	ds_read_b128 v[206:209], v201 offset:49152
	ds_read_b128 v[222:225], v201 offset:57344
	v_exp_f32_e32 v204, v89
	v_add_f32_e32 v88, v85, v88
	v_exp_f32_e32 v205, v90
	v_add_f32_e32 v88, v86, v88
	v_add_f32_e32 v88, v87, v88
	v_add_f32_e32 v88, v203, v88
	v_exp_f32_e32 v210, v93
	v_add_f32_e32 v88, v204, v88
	v_exp_f32_e32 v211, v94
	s_waitcnt lgkmcnt(1)
	v_mfma_f32_32x32x16_bf16 v[96:111], v[206:209], v[112:115], v[96:111]
	v_add_f32_e32 v88, v205, v88
	v_exp_f32_e32 v212, v95
	v_add_f32_e32 v88, v240, v88
	v_add_f32_e32 v88, v241, v88
	v_add_f32_e32 v88, v210, v88
	v_add_f32_e32 v88, v211, v88
	v_add_f32_e32 v201, v212, v88
	s_waitcnt lgkmcnt(0)
	v_mfma_f32_32x32x16_bf16 v[64:79], v[222:225], v[112:115], v[64:79]
	v_cvt_pk_bf16_f32 v88, v199, v221
	v_cvt_pk_bf16_f32 v89, v226, v227
	v_cvt_pk_bf16_f32 v90, v228, v229
	v_cvt_pk_bf16_f32 v93, v234, v235
	v_cvt_pk_bf16_f32 v94, v236, v237
	v_cvt_pk_bf16_f32 v95, v238, v239
	v_cvt_pk_bf16_f32 v80, v80, v81
	v_cvt_pk_bf16_f32 v81, v82, v83
	v_cvt_pk_bf16_f32 v82, v84, v85
	v_cvt_pk_bf16_f32 v83, v86, v87
	v_cvt_pk_bf16_f32 v84, v203, v204
	v_cvt_pk_bf16_f32 v85, v205, v240
	v_cvt_pk_bf16_f32 v86, v241, v210
	v_cvt_pk_bf16_f32 v87, v211, v212
	s_cmpk_gt_u32 s6, 0x7c
	s_cselect_b64 s[4:5], -1, 0
	s_and_b64 vcc, exec, s[4:5]
	s_cbranch_vccnz .Lattn_a0_lastw
	global_load_dwordx4 v[132:135], v244, s[98:99]
	global_load_dwordx4 v[128:131], v242, s[98:99]
	global_load_dwordx4 v[140:143], v245, s[98:99]
	global_load_dwordx4 v[136:139], v243, s[98:99]
	s_add_u32 s98, s98, 0x10000
	s_addc_u32 s99, s99, 0
.LBB0_431:
	v_add_u32_e32 v203, s16, v181
	ds_read_b64_tr_b16 v[204:205], v203 offset:0
	ds_read_b64_tr_b16 v[206:207], v203 offset:0x100
	ds_read_b64_tr_b16 v[208:209], v203 offset:0x1000
	ds_read_b64_tr_b16 v[210:211], v203 offset:0x1100
	ds_read_b64_tr_b16 v[222:223], v203 offset:0x2000
	ds_read_b64_tr_b16 v[224:225], v203 offset:0x2100
	ds_read_b64_tr_b16 v[226:227], v203 offset:0x3000
	ds_read_b64_tr_b16 v[228:229], v203 offset:0x3100
	s_waitcnt lgkmcnt(0)
	v_mfma_f32_32x32x16_bf16 v[0:15], v[88:91], v[204:207], v[0:15]
	v_max_f32_e32 v199, v96, v97
	ds_read_b64_tr_b16 v[204:205], v203 offset:0x200
	ds_read_b64_tr_b16 v[206:207], v203 offset:0x300
	v_max3_f32 v199, v199, v98, v99
	v_max3_f32 v199, v199, v100, v101
	v_mfma_f32_32x32x16_bf16 v[0:15], v[92:95], v[208:211], v[0:15]
	ds_read_b64_tr_b16 v[208:209], v203 offset:0x1200
	ds_read_b64_tr_b16 v[210:211], v203 offset:0x1300
	v_max3_f32 v199, v199, v102, v103
	v_max3_f32 v199, v199, v104, v105
	v_max3_f32 v199, v199, v106, v107
	v_max3_f32 v199, v199, v108, v109
	v_max3_f32 v199, v199, v110, v111
	v_mfma_f32_32x32x16_bf16 v[0:15], v[80:83], v[222:225], v[0:15]
	ds_read_b64_tr_b16 v[222:223], v203 offset:0x2200
	ds_read_b64_tr_b16 v[224:225], v203 offset:0x2300
	ds_read_b64_tr_b16 v[230:231], v203 offset:0x3200
	ds_read_b64_tr_b16 v[232:233], v203 offset:0x3300
	v_mfma_f32_32x32x16_bf16 v[0:15], v[84:87], v[226:229], v[0:15]
	s_waitcnt lgkmcnt(6)
	v_mfma_f32_32x32x16_bf16 v[48:63], v[88:91], v[204:207], v[48:63]
	v_max3_f32 v199, v199, v64, v65
	v_max3_f32 v199, v199, v66, v67
	ds_read_b64_tr_b16 v[206:207], v203 offset:0x400
	v_max3_f32 v199, v199, v68, v69
	v_max3_f32 v199, v199, v70, v71
	v_max3_f32 v199, v199, v72, v73
	v_max3_f32 v199, v199, v74, v75
	s_waitcnt lgkmcnt(5)
	v_mfma_f32_32x32x16_bf16 v[48:63], v[92:95], v[208:211], v[48:63]
	ds_read_b64_tr_b16 v[208:209], v203 offset:0x500
	ds_read_b64_tr_b16 v[210:211], v203 offset:0x1400
	ds_read_b64_tr_b16 v[212:213], v203 offset:0x1500
	v_max3_f32 v199, v199, v76, v77
	v_max3_f32 v204, v199, v78, v79
	s_waitcnt lgkmcnt(6)
	v_mfma_f32_32x32x16_bf16 v[48:63], v[80:83], v[222:225], v[48:63]
	ds_read_b64_tr_b16 v[222:223], v203 offset:0x2400
	ds_read_b64_tr_b16 v[224:225], v203 offset:0x2500
	ds_read_b64_tr_b16 v[226:227], v203 offset:0x3400
	ds_read_b64_tr_b16 v[228:229], v203 offset:0x3500
	s_waitcnt lgkmcnt(8)
	v_mfma_f32_32x32x16_bf16 v[48:63], v[84:87], v[230:233], v[48:63]
	s_waitcnt lgkmcnt(6)
	v_mfma_f32_32x32x16_bf16 v[32:47], v[88:91], v[206:209], v[32:47]
	v_cmp_ge_f32_e32 vcc, s63, v204
	s_cmp_eq_u64 vcc, exec
	v_mov_b32_e32 v199, 1.0
	s_mov_b32 s100, 0
	s_waitcnt lgkmcnt(4)
	v_mfma_f32_32x32x16_bf16 v[32:47], v[92:95], v[210:213], v[32:47]
	s_waitcnt lgkmcnt(2)
	v_mfma_f32_32x32x16_bf16 v[32:47], v[80:83], v[222:225], v[32:47]
	s_waitcnt lgkmcnt(0)
	v_mfma_f32_32x32x16_bf16 v[32:47], v[84:87], v[226:229], v[32:47]
	s_cbranch_scc0 .LBB0_439
.LBB0_432:
	ds_read_b64_tr_b16 v[204:205], v203 offset:0x600
	ds_read_b64_tr_b16 v[206:207], v203 offset:0x700
	ds_read_b64_tr_b16 v[208:209], v203 offset:0x1600
	ds_read_b64_tr_b16 v[210:211], v203 offset:0x1700
	ds_read_b64_tr_b16 v[222:223], v203 offset:0x2600
	ds_read_b64_tr_b16 v[224:225], v203 offset:0x2700
	ds_read_b64_tr_b16 v[226:227], v203 offset:0x3600
	ds_read_b64_tr_b16 v[228:229], v203 offset:0x3700
	s_add_i32 s16, s18, 1
	s_cmp_lg_u32 s18, 2
	s_cselect_b32 s19, s16, 0
	s_waitcnt lgkmcnt(6)
	v_mfma_f32_32x32x16_bf16 v[16:31], v[88:91], v[204:207], v[16:31]
	s_lshl_b32 s16, s19, 14
	s_add_i32 s16, s16, 16
	s_waitcnt vmcnt(4)
	v_add_u32_e32 v88, s16, v184
	ds_write_b128 v88, v[144:147]
	s_waitcnt lgkmcnt(5)
	v_mfma_f32_32x32x16_bf16 v[16:31], v[92:95], v[208:211], v[16:31]
	s_waitcnt lgkmcnt(3)
	v_mfma_f32_32x32x16_bf16 v[16:31], v[80:83], v[222:225], v[16:31]
	v_add_u32_e32 v80, s16, v186
	ds_write_b128 v80, v[148:151]
	v_add_u32_e32 v80, s16, v183
	ds_write_b128 v80, v[152:155] offset:49152
	v_add_u32_e32 v80, s16, v188
	ds_write_b128 v80, v[156:159] offset:49152
	s_waitcnt lgkmcnt(4)
	v_mfma_f32_32x32x16_bf16 v[16:31], v[84:87], v[226:229], v[16:31]
	s_cmp_eq_u32 s101, 0
	s_cbranch_scc1 .Lst_a0_e1
	s_waitcnt lgkmcnt(0)
	s_barrier
.Lst_a0_e1:
	s_cmp_eq_u32 s100, 0
	s_cbranch_scc1 .LBB0_436
	s_and_saveexec_b64 s[16:17], s[0:1]
	ds_write_b32 v179, v199 offset:128
	s_or_b64 exec, exec, s[16:17]
	s_waitcnt lgkmcnt(0)
	v_add_u32_e32 v92, v177, v176
	ds_read_b128 v[80:83], v92 offset:224
	ds_read_b128 v[84:87], v92 offset:192
	ds_read_b128 v[88:91], v92 offset:160
	ds_read_b128 v[92:95], v92 offset:128
	s_waitcnt lgkmcnt(3)
	v_pk_mul_f32 v[12:13], v[12:13], v[80:81]
	s_waitcnt lgkmcnt(2)
	v_pk_mul_f32 v[8:9], v[8:9], v[84:85]
	s_waitcnt lgkmcnt(1)
	v_pk_mul_f32 v[4:5], v[4:5], v[88:89]
	v_pk_mul_f32 v[14:15], v[14:15], v[82:83]
	v_pk_mul_f32 v[10:11], v[10:11], v[86:87]
	v_pk_mul_f32 v[6:7], v[6:7], v[90:91]
	s_waitcnt lgkmcnt(0)
	v_pk_mul_f32 v[2:3], v[2:3], v[94:95]
	v_pk_mul_f32 v[0:1], v[0:1], v[92:93]
	v_pk_mul_f32 v[60:61], v[60:61], v[80:81]
	v_pk_mul_f32 v[56:57], v[56:57], v[84:85]
	v_pk_mul_f32 v[52:53], v[52:53], v[88:89]
	v_pk_mul_f32 v[62:63], v[62:63], v[82:83]
	v_pk_mul_f32 v[58:59], v[58:59], v[86:87]
	v_pk_mul_f32 v[54:55], v[54:55], v[90:91]
	v_pk_mul_f32 v[50:51], v[50:51], v[94:95]
	v_pk_mul_f32 v[48:49], v[48:49], v[92:93]
	v_pk_mul_f32 v[44:45], v[44:45], v[80:81]
	v_pk_mul_f32 v[40:41], v[40:41], v[84:85]
	v_pk_mul_f32 v[36:37], v[36:37], v[88:89]
	v_pk_mul_f32 v[46:47], v[46:47], v[82:83]
	v_pk_mul_f32 v[42:43], v[42:43], v[86:87]
	v_pk_mul_f32 v[38:39], v[38:39], v[90:91]
	v_pk_mul_f32 v[34:35], v[34:35], v[94:95]
	v_pk_mul_f32 v[32:33], v[32:33], v[92:93]
	v_pk_mul_f32 v[28:29], v[28:29], v[80:81]
	v_pk_mul_f32 v[24:25], v[24:25], v[84:85]
	v_pk_mul_f32 v[20:21], v[20:21], v[88:89]
	v_pk_mul_f32 v[30:31], v[30:31], v[82:83]
	v_pk_mul_f32 v[26:27], v[26:27], v[86:87]
	v_pk_mul_f32 v[22:23], v[22:23], v[90:91]
	v_pk_mul_f32 v[18:19], v[18:19], v[94:95]
	v_pk_mul_f32 v[16:17], v[16:17], v[92:93]
.LBB0_436:
	v_exp_f32_e32 v152, v96
	v_exp_f32_e32 v153, v97
	v_exp_f32_e32 v154, v98
	v_exp_f32_e32 v155, v99
	v_exp_f32_e32 v156, v100
	v_exp_f32_e32 v157, v101
	v_exp_f32_e32 v158, v102
	v_exp_f32_e32 v159, v103
	v_exp_f32_e32 v144, v104
	v_exp_f32_e32 v145, v105
	v_exp_f32_e32 v146, v106
	v_exp_f32_e32 v147, v107
	v_exp_f32_e32 v148, v108
	v_exp_f32_e32 v149, v109
	v_exp_f32_e32 v150, v110
	v_exp_f32_e32 v151, v111
	v_fma_f32 v80, v196, v180, v197
	v_fma_f32 v180, v80, v200, v201
	s_add_i32 s6, s6, 2
	s_and_b64 vcc, exec, s[4:5]
	s_waitcnt lgkmcnt(0)
	s_cmp_lg_u32 s101, 0
	s_cbranch_scc1 .Lst_a0_l1
	s_barrier

.LBB0_438:
	v_mov_b32_e32 v201, v200
	s_nop 1
	v_permlane32_swap_b32_e32 v200, v201
	v_max_f32_e32 v200, v200, v201
	v_max_f32_e32 v202, 0, v200
	v_exp_f32_e64 v200, -v202
	v_add_f32_e32 v195, v195, v202
	v_pk_add_f32 v[96:97], v[96:97], v[202:203] op_sel_hi:[1,0] neg_lo:[0,1] neg_hi:[0,1]
	v_pk_add_f32 v[98:99], v[98:99], v[202:203] op_sel_hi:[1,0] neg_lo:[0,1] neg_hi:[0,1]
	v_pk_add_f32 v[100:101], v[100:101], v[202:203] op_sel_hi:[1,0] neg_lo:[0,1] neg_hi:[0,1]
	v_pk_add_f32 v[102:103], v[102:103], v[202:203] op_sel_hi:[1,0] neg_lo:[0,1] neg_hi:[0,1]
	v_pk_add_f32 v[104:105], v[104:105], v[202:203] op_sel_hi:[1,0] neg_lo:[0,1] neg_hi:[0,1]
	v_pk_add_f32 v[106:107], v[106:107], v[202:203] op_sel_hi:[1,0] neg_lo:[0,1] neg_hi:[0,1]
	v_pk_add_f32 v[108:109], v[108:109], v[202:203] op_sel_hi:[1,0] neg_lo:[0,1] neg_hi:[0,1]
	v_pk_add_f32 v[110:111], v[110:111], v[202:203] op_sel_hi:[1,0] neg_lo:[0,1] neg_hi:[0,1]
	v_sub_f32_e32 v95, v95, v202
	v_sub_f32_e32 v94, v94, v202
	v_sub_f32_e32 v93, v93, v202
	v_sub_f32_e32 v92, v92, v202
	v_sub_f32_e32 v91, v91, v202
	v_sub_f32_e32 v90, v90, v202
	v_sub_f32_e32 v89, v89, v202
	v_sub_f32_e32 v88, v88, v202
	v_sub_f32_e32 v87, v87, v202
	v_sub_f32_e32 v86, v86, v202
	v_sub_f32_e32 v85, v85, v202
	v_sub_f32_e32 v84, v84, v202
	v_sub_f32_e32 v83, v83, v202
	v_sub_f32_e32 v82, v82, v202
	v_sub_f32_e32 v81, v81, v202
	v_sub_f32_e32 v80, v80, v202
	v_cmp_gt_f32_e32 vcc, 1.0, v200
	s_or_b32 s100, vcc_lo, vcc_hi
	s_branch .LBB0_425
.LBB0_439:
	v_mov_b32_e32 v199, v204
	s_nop 1
	v_permlane32_swap_b32_e32 v204, v199
	v_max_f32_e32 v199, v204, v199
	v_max_f32_e32 v204, 0, v199
	v_exp_f32_e64 v199, -v204
	v_add_f32_e32 v195, v195, v204
	v_pk_add_f32 v[96:97], v[96:97], v[204:205] op_sel_hi:[1,0] neg_lo:[0,1] neg_hi:[0,1]
	v_pk_add_f32 v[98:99], v[98:99], v[204:205] op_sel_hi:[1,0] neg_lo:[0,1] neg_hi:[0,1]
	v_pk_add_f32 v[100:101], v[100:101], v[204:205] op_sel_hi:[1,0] neg_lo:[0,1] neg_hi:[0,1]
	v_pk_add_f32 v[102:103], v[102:103], v[204:205] op_sel_hi:[1,0] neg_lo:[0,1] neg_hi:[0,1]
	v_pk_add_f32 v[104:105], v[104:105], v[204:205] op_sel_hi:[1,0] neg_lo:[0,1] neg_hi:[0,1]
	v_pk_add_f32 v[106:107], v[106:107], v[204:205] op_sel_hi:[1,0] neg_lo:[0,1] neg_hi:[0,1]
	v_pk_add_f32 v[108:109], v[108:109], v[204:205] op_sel_hi:[1,0] neg_lo:[0,1] neg_hi:[0,1]
	v_pk_add_f32 v[110:111], v[110:111], v[204:205] op_sel_hi:[1,0] neg_lo:[0,1] neg_hi:[0,1]
	v_sub_f32_e32 v79, v79, v204
	v_sub_f32_e32 v78, v78, v204
	v_sub_f32_e32 v77, v77, v204
	v_sub_f32_e32 v76, v76, v204
	v_sub_f32_e32 v75, v75, v204
	v_sub_f32_e32 v74, v74, v204
	v_sub_f32_e32 v73, v73, v204
	v_sub_f32_e32 v72, v72, v204
	v_sub_f32_e32 v71, v71, v204
	v_sub_f32_e32 v70, v70, v204
	v_sub_f32_e32 v69, v69, v204
	v_sub_f32_e32 v68, v68, v204
	v_sub_f32_e32 v67, v67, v204
	v_sub_f32_e32 v66, v66, v204
	v_sub_f32_e32 v65, v65, v204
	v_sub_f32_e32 v64, v64, v204
	v_cmp_gt_f32_e32 vcc, 1.0, v199
	s_or_b32 s100, vcc_lo, vcc_hi
	s_branch .LBB0_432

.LBB0_805:
	s_lshl_b32 s0, s39, 10
	s_and_b32 s6, s0, 0x800000
	s_lshl_b32 s0, s43, 1
	s_and_b32 s65, s0, 0x300
	s_lshl_b32 s0, s2, 11
	s_lshl_b32 s1, s2, 4
	s_and_b32 s0, s0, 0x2000
	s_and_b32 s1, s1, 0xffffff80
	s_add_i32 s1, s0, s1
	v_or_b32_e32 v171, s1, v170
	v_or_b32_e32 v0, v171, v169
	v_ashrrev_i32_e32 v1, 31, v0
	s_lshl_b32 s1, s2, 7
	v_lshlrev_b64 v[0:1], 10, v[0:1]
	s_and_b32 s64, s1, 0x180
	v_lshl_add_u64 v[0:1], s[86:87], 0, v[0:1]
	s_lshl_b32 s4, s64, 1
	s_mov_b32 s5, s7
	v_lshl_add_u64 v[0:1], v[0:1], 0, s[4:5]
	s_lshl_b32 s5, s0, 10
	s_add_u32 s0, s33, s5
	s_addc_u32 s1, s34, 0
	s_add_u32 s0, s0, s4
	v_mov_b32_e32 v174, v168
	v_lshl_add_u64 v[0:1], v[160:161], 1, v[0:1]
	s_addc_u32 s1, s1, 0
	v_lshl_add_u64 v[0:1], v[0:1], 0, v[162:163]
	v_ashrrev_i32_e32 v16, 4, v174
	s_add_u32 s5, s35, s5
	v_lshlrev_b32_e32 v20, 3, v174
	v_add_u32_e32 v18, 32, v16
	s_addc_u32 s16, s38, 0
	global_load_dwordx4 v[124:127], v[0:1], off
	global_load_dwordx4 v[120:123], v[0:1], off offset:32
	global_load_dwordx4 v[116:119], v[0:1], off offset:64
	global_load_dwordx4 v[112:115], v[0:1], off offset:96
	v_and_b32_e32 v0, 0x78, v20
	v_ashrrev_i32_e32 v17, 31, v16
	v_ashrrev_i32_e32 v19, 31, v18
	s_add_u32 s4, s5, s4
	v_lshlrev_b32_e32 v21, 1, v0
	v_lshlrev_b64 v[48:49], 10, v[16:17]
	v_lshlrev_b64 v[12:13], 10, v[18:19]
	s_addc_u32 s5, s16, 0
	v_or_b32_e32 v50, v48, v21
	v_mov_b32_e32 v51, v49
	v_or_b32_e32 v12, v12, v21
	v_lshl_add_u64 v[0:1], s[4:5], 0, v[50:51]
	v_lshl_add_u64 v[4:5], s[4:5], 0, v[12:13]
	s_barrier
	global_load_dwordx4 v[0:3], v[0:1], off
	s_nop 0
	global_load_dwordx4 v[4:7], v[4:5], off
	v_lshl_add_u64 v[8:9], s[0:1], 0, v[50:51]
	global_load_dwordx4 v[8:11], v[8:9], off
	v_lshl_add_u64 v[12:13], s[0:1], 0, v[12:13]
	global_load_dwordx4 v[12:15], v[12:13], off
	v_and_b32_e32 v22, 0xfffff0, v16
	v_lshlrev_b32_e32 v23, 1, v16
	v_lshrrev_b32_e32 v24, 1, v16
	v_and_b32_e32 v25, 3, v16
	v_and_or_b32 v22, v23, 8, v22
	v_and_or_b32 v23, v24, 4, v25
	v_and_b32_e32 v24, 0xfffff0, v18
	v_lshlrev_b32_e32 v25, 1, v18
	v_and_b32_e32 v17, 0x70, v174
	v_bfe_u32 v20, v20, 5, 2
	v_lshlrev_b32_e32 v16, 8, v16
	v_lshrrev_b32_e32 v22, 1, v22
	v_and_or_b32 v24, v25, 8, v24
	v_bitop3_b32 v183, v21, v16, v17 bitop3:0xde
	v_or_b32_e32 v16, v22, v20
	v_lshrrev_b32_e32 v22, 1, v24
	v_lshlrev_b32_e32 v23, 6, v23
	v_and_b32_e32 v26, 48, v21
	v_lshlrev_b32_e32 v16, 9, v16
	v_or_b32_e32 v20, v22, v20
	v_or3_b32 v184, v16, v23, v26
	v_lshlrev_b32_e32 v16, 9, v20
	v_bfe_u32 v172, v174, 5, 1
	v_ashrrev_i32_e32 v175, 8, v174
	v_lshlrev_b32_e32 v52, 4, v174
	v_or3_b32 v186, v16, v23, v26
	v_add_u32_e32 v84, 16, v184
	v_and_b32_e32 v173, 31, v174
	v_lshlrev_b32_e32 v19, 7, v175
	v_add_u32_e32 v24, 16, v183
	v_add_u32_e32 v85, 16, v186
	s_waitcnt vmcnt(0)
	v_lshlrev_b32_e32 v176, 4, v172
	v_lshlrev_b32_e32 v190, 8, v173
	v_and_b32_e32 v86, 63, v174
	v_lshl_add_u64 v[60:61], v[50:51], 0, s[14:15]
	v_lshl_add_u64 v[64:65], v[50:51], 0, s[36:37]
	v_lshl_add_u64 v[56:57], s[4:5], 0, v[64:65]
	v_lshl_add_u64 v[64:65], s[0:1], 0, v[64:65]
	s_cmp_lg_u32 16, -1
	s_cselect_b32 s16, 16, 0
	s_mov_b32 s17, s7
	s_mov_b32 s18, s7
	s_mov_b32 s19, s7
	s_mov_b32 s20, s7
	s_waitcnt vmcnt(3)
	ds_write_b128 v84, v[0:3]
	s_waitcnt vmcnt(2)
	ds_write_b128 v85, v[4:7]
	s_waitcnt vmcnt(1)
	ds_write_b128 v24, v[8:11] offset:49152
	v_and_b32_e32 v8, 0x70, v52
	v_lshlrev_b32_e32 v0, 8, v18
	v_bitop3_b32 v182, v176, v8, v19 bitop3:0x36
	v_bitop3_b32 v188, v21, v0, v17 bitop3:0xde
	v_add_u32_e32 v185, v182, v190
	v_add_u32_e32 v0, 16, v188
	v_add_u32_e32 v4, 16, v185
	s_waitcnt vmcnt(0)
	ds_write_b128 v0, v[12:15] offset:49152
	s_waitcnt lgkmcnt(0)
	s_barrier
	ds_read_b128 v[0:3], v4 offset:49152
	ds_read_b128 v[4:7], v4 offset:57344
	v_or_b32_e32 v9, v176, v19
	v_bitop3_b32 v187, v9, v8, 32 bitop3:0x36
	v_add_u32_e32 v189, v187, v190
	s_waitcnt lgkmcnt(0)
	v_mfma_f32_32x32x16_bf16 v[16:31], v[4:7], v[124:127], 0
	v_add_u32_e32 v4, 16, v189
	v_bitop3_b32 v193, v9, v8, s3 bitop3:0x36
	v_bitop3_b32 v191, v9, v8, 64 bitop3:0x36
	v_add_u32_e32 v194, v193, v190
	v_add_u32_e32 v192, v191, v190
	v_add_u32_e32 v8, 16, v194
	v_and_b32_e32 v5, 0x3fffffc0, v174
	v_mfma_f32_32x32x16_bf16 v[32:47], v[0:3], v[124:127], 0
	ds_read_b128 v[0:3], v4 offset:49152
	v_and_b32_e32 v11, 0xc0, v52
	v_add_u32_e32 v13, 16, v192
	ds_read_b128 v[52:55], v8 offset:57344
	v_lshl_add_u32 v177, v5, 2, s50
	ds_read_b128 v[4:7], v4 offset:57344
	v_lshlrev_b32_e32 v10, 3, v86
	s_waitcnt lgkmcnt(2)
	v_mfma_f32_32x32x16_bf16 v[32:47], v[0:3], v[120:123], v[32:47]
	v_lshlrev_b32_e32 v0, 1, v174
	v_and_b32_e32 v12, 32, v0
	ds_read_b128 v[0:3], v13 offset:49152
	v_and_or_b32 v11, v10, 24, v11
	s_mov_b32 s21, s7
	s_mov_b32 s22, s7
	s_mov_b32 s23, s7
	s_waitcnt lgkmcnt(0)
	v_mfma_f32_32x32x16_bf16 v[32:47], v[0:3], v[116:119], v[32:47]
	ds_read_b128 v[0:3], v8 offset:49152
	s_mov_b32 s24, s7
	s_mov_b32 s25, s7
	s_mov_b32 s26, s7
	s_mov_b32 s27, s7
	s_mov_b32 s28, s7
	s_mov_b32 s29, s7
	v_mfma_f32_32x32x16_bf16 v[16:31], v[4:7], v[120:123], v[16:31]
	v_and_b32_e32 v4, 0x100, v10
	v_lshlrev_b32_e32 v4, 3, v4
	v_or3_b32 v178, v11, v12, v4
	ds_read_b128 v[4:7], v13 offset:57344
	v_add_u32_e32 v181, s16, v178
	s_mov_b32 s16, s7
	s_mov_b32 s30, s7
	s_mov_b32 s31, s7
	s_waitcnt lgkmcnt(0)
	v_mfma_f32_32x32x16_bf16 v[16:31], v[4:7], v[116:119], v[16:31]
	v_lshl_add_u32 v179, v173, 2, v177
	v_mov_b32_e32 v196, 1.0
	v_mov_b32_e32 v180, 0
	v_mfma_f32_32x32x16_bf16 v[32:47], v[0:3], v[112:115], v[32:47]
	v_mov_b64_e32 v[0:1], s[16:17]
	v_mov_b64_e32 v[14:15], s[30:31]
	v_mov_b64_e32 v[2:3], s[18:19]
	v_mov_b64_e32 v[4:5], s[20:21]
	v_mov_b64_e32 v[6:7], s[22:23]
	v_mov_b64_e32 v[8:9], s[24:25]
	v_mov_b64_e32 v[10:11], s[26:27]
	v_mfma_f32_32x32x16_bf16 v[16:31], v[52:55], v[112:115], v[16:31]
	s_nop 3
	v_max_f32_e32 v52, v33, v33
	v_max_f32_e32 v53, v32, v32
	v_max_f32_e32 v52, v53, v52
	v_max3_f32 v52, v52, v34, v35
	v_max3_f32 v52, v52, v36, v37
	v_max3_f32 v52, v52, v38, v39
	v_max3_f32 v52, v52, v40, v41
	v_max3_f32 v52, v52, v42, v43
	v_max3_f32 v52, v52, v44, v45
	v_max3_f32 v66, v52, v46, v47
	v_lshl_add_u64 v[52:53], s[4:5], 0, v[60:61]
	v_lshl_add_u64 v[60:61], s[0:1], 0, v[60:61]
	global_load_dwordx4 v[52:55], v[52:53], off
	s_nop 0
	global_load_dwordx4 v[56:59], v[56:57], off
	v_mov_b64_e32 v[12:13], s[28:29]
	global_load_dwordx4 v[60:63], v[60:61], off
	s_mov_b32 s19, 1
	global_load_dwordx4 v[80:83], v[64:65], off
	v_max3_f32 v64, v66, v16, v17
	v_max3_f32 v64, v64, v18, v19
	v_max3_f32 v64, v64, v20, v21
	v_max3_f32 v64, v64, v22, v23
	v_max3_f32 v64, v64, v24, v25
	v_max3_f32 v64, v64, v26, v27
	v_max3_f32 v64, v64, v28, v29
	v_max3_f32 v70, v64, v30, v31
	v_lshl_add_u64 v[64:65], v[50:51], 0, s[40:41]
	v_lshl_add_u64 v[66:67], s[0:1], 0, v[64:65]
	v_lshl_add_u64 v[50:51], v[50:51], 0, s[44:45]
	v_lshl_add_u64 v[64:65], s[4:5], 0, v[64:65]
	v_lshl_add_u64 v[68:69], s[0:1], 0, v[50:51]
	global_load_dwordx4 v[136:139], v[66:67], off
	global_load_dwordx4 v[128:131], v[68:69], off
	v_lshl_add_u64 v[50:51], s[4:5], 0, v[50:51]
	global_load_dwordx4 v[140:143], v[64:65], off
	global_load_dwordx4 v[132:135], v[50:51], off
	v_mov_b32_e32 v71, v70
	s_nop 1
	v_permlane32_swap_b32_e32 v70, v71
	v_max_f32_e32 v50, v71, v71
	v_max_f32_e32 v51, v70, v70
	v_max_f32_e32 v50, v51, v50
	v_sub_f32_e32 v64, v16, v50
	v_add_u32_e32 v16, s58, v183
	v_sub_f32_e32 v32, v32, v50
	v_sub_f32_e32 v33, v33, v50
	v_sub_f32_e32 v34, v34, v50
	v_sub_f32_e32 v35, v35, v50
	v_sub_f32_e32 v36, v36, v50
	v_sub_f32_e32 v37, v37, v50
	v_sub_f32_e32 v38, v38, v50
	v_sub_f32_e32 v39, v39, v50
	v_sub_f32_e32 v40, v40, v50
	v_sub_f32_e32 v41, v41, v50
	v_sub_f32_e32 v42, v42, v50
	v_sub_f32_e32 v43, v43, v50
	v_sub_f32_e32 v44, v44, v50
	v_sub_f32_e32 v45, v45, v50
	v_sub_f32_e32 v46, v46, v50
	v_sub_f32_e32 v47, v47, v50
	v_sub_f32_e32 v66, v18, v50
	s_waitcnt vmcnt(4)
	s_waitcnt vmcnt(7)
	ds_write_b128 v84, v[52:55] offset:16384
	s_waitcnt vmcnt(6)
	ds_write_b128 v85, v[56:59] offset:16384
	v_and_b32_e32 v18, 15, v174
	s_waitcnt vmcnt(5)
	ds_write_b128 v16, v[60:63]
	v_add_u32_e32 v16, s58, v188
	v_sub_f32_e32 v65, v17, v50
	v_exp_f32_e32 v152, v32
	v_exp_f32_e32 v153, v33
	v_exp_f32_e32 v154, v34
	v_exp_f32_e32 v155, v35
	v_exp_f32_e32 v156, v36
	v_exp_f32_e32 v157, v37
	v_exp_f32_e32 v158, v38
	v_exp_f32_e32 v159, v39
	v_exp_f32_e32 v144, v40
	v_exp_f32_e32 v145, v41
	v_exp_f32_e32 v146, v42
	v_exp_f32_e32 v147, v43
	v_exp_f32_e32 v148, v44
	v_exp_f32_e32 v149, v45
	v_exp_f32_e32 v150, v46
	v_exp_f32_e32 v151, v47
	s_waitcnt vmcnt(4)
	ds_write_b128 v16, v[80:83]
	v_lshl_add_u64 v[16:17], s[6:7], 0, v[48:49]
	v_lshlrev_b32_e32 v18, 4, v18
	v_or3_b32 v16, v16, s65, v18
	v_add_f32_e32 v195, 0, v50
	v_sub_f32_e32 v79, v31, v50
	v_sub_f32_e32 v78, v30, v50
	v_sub_f32_e32 v77, v29, v50
	v_sub_f32_e32 v76, v28, v50
	v_sub_f32_e32 v75, v27, v50
	v_sub_f32_e32 v74, v26, v50
	v_sub_f32_e32 v73, v25, v50
	v_sub_f32_e32 v72, v24, v50
	v_sub_f32_e32 v71, v23, v50
	v_sub_f32_e32 v70, v22, v50
	v_sub_f32_e32 v69, v21, v50
	v_sub_f32_e32 v68, v20, v50
	v_sub_f32_e32 v67, v19, v50
	v_lshl_add_u64 v[166:167], s[12:13], 0, v[16:17]
	v_mov_b64_e32 v[62:63], v[14:15]
	v_mov_b64_e32 v[46:47], v[14:15]
	v_mov_b64_e32 v[30:31], v[14:15]
	v_cmp_gt_u32_e64 s[0:1], 32, v86
	v_mov_b64_e32 v[60:61], v[12:13]
	v_mov_b64_e32 v[58:59], v[10:11]
	v_mov_b64_e32 v[56:57], v[8:9]
	v_mov_b64_e32 v[54:55], v[6:7]
	v_mov_b64_e32 v[52:53], v[4:5]
	v_mov_b64_e32 v[50:51], v[2:3]
	v_mov_b64_e32 v[48:49], v[0:1]
	v_mov_b64_e32 v[44:45], v[12:13]
	v_mov_b64_e32 v[42:43], v[10:11]
	v_mov_b64_e32 v[40:41], v[8:9]
	v_mov_b64_e32 v[38:39], v[6:7]
	v_mov_b64_e32 v[36:37], v[4:5]
	v_mov_b64_e32 v[34:35], v[2:3]
	v_mov_b64_e32 v[32:33], v[0:1]
	v_mov_b64_e32 v[28:29], v[12:13]
	v_mov_b64_e32 v[26:27], v[10:11]
	v_mov_b64_e32 v[24:25], v[8:9]
	v_mov_b64_e32 v[22:23], v[6:7]
	v_mov_b64_e32 v[20:21], v[4:5]
	v_mov_b64_e32 v[18:19], v[2:3]
	v_mov_b64_e32 v[16:17], v[0:1]
	s_mov_b32 s6, 1
	s_mov_b32 s18, 0
	s_waitcnt lgkmcnt(0)
	s_barrier
	v_add_co_u32_e32 v242, vcc, s61, v166
	s_nop 1
	v_addc_co_u32_e32 v243, vcc, -1, v167, vcc
	s_nop 0
	v_readfirstlane_b32 s98, v242
	v_readfirstlane_b32 s99, v243
	s_nop 1
	v_subrev_u32_e32 v242, s98, v242
	v_add_u32_e32 v243, 0x8000, v242
	v_add_u32_e32 v244, 0x1000000, v242
	v_add_u32_e32 v245, 0x1008000, v242
	v_readfirstlane_b32 s101, v214
	s_lshr_b32 s101, s101, 8
